# scan: o-tile LDS staging XOR-swizzled by row group (conflict-free ds_write_b16), on top of g1 store widening
# speedup vs baseline: 1.0493x; 1.0028x over previous
.LBB0_1092:
	v_lshlrev_b32_e32 v146, 16, v32
	v_and_b32_e32 v147, 0xffff0000, v32
	v_lshlrev_b32_e32 v148, 16, v33
	v_and_b32_e32 v149, 0xffff0000, v33
	v_xor_b32_e32 v32, 0x80000000, v1
	v_xor_b32_e32 v33, 0x80000000, v0
	v_cvt_pk_bf16_f32 v150, v33, v32
	v_xor_b32_e32 v32, 0x80000000, v2
	v_xor_b32_e32 v33, 0x80000000, v3
	v_cvt_pk_bf16_f32 v151, v32, v33
	v_xor_b32_e32 v32, 0x80000000, v4
	v_xor_b32_e32 v33, 0x80000000, v5
	v_cvt_pk_bf16_f32 v152, v32, v33
	v_xor_b32_e32 v32, 0x80000000, v6
	v_xor_b32_e32 v33, 0x80000000, v7
	v_cvt_pk_bf16_f32 v153, v32, v33
	v_xor_b32_e32 v32, 0x80000000, v8
	v_xor_b32_e32 v33, 0x80000000, v9
	v_cvt_pk_bf16_f32 v154, v32, v33
	v_xor_b32_e32 v32, 0x80000000, v10
	v_xor_b32_e32 v33, 0x80000000, v11
	v_cvt_pk_bf16_f32 v155, v32, v33
	v_xor_b32_e32 v32, 0x80000000, v12
	v_xor_b32_e32 v33, 0x80000000, v13
	v_cvt_pk_bf16_f32 v156, v32, v33
	v_xor_b32_e32 v32, 0x80000000, v14
	v_xor_b32_e32 v33, 0x80000000, v15
	v_cvt_pk_bf16_f32 v157, v32, v33
	v_xor_b32_e32 v32, 0x80000000, v16
	v_xor_b32_e32 v33, 0x80000000, v17
	v_cvt_pk_bf16_f32 v158, v32, v33
	v_xor_b32_e32 v32, 0x80000000, v18
	v_xor_b32_e32 v33, 0x80000000, v19
	v_cvt_pk_bf16_f32 v159, v32, v33
	v_xor_b32_e32 v32, 0x80000000, v20
	v_xor_b32_e32 v33, 0x80000000, v21
	v_cvt_pk_bf16_f32 v160, v32, v33
	v_xor_b32_e32 v32, 0x80000000, v22
	v_xor_b32_e32 v33, 0x80000000, v23
	v_cvt_pk_bf16_f32 v161, v32, v33
	v_xor_b32_e32 v32, 0x80000000, v28
	v_xor_b32_e32 v33, 0x80000000, v29
	s_bitcmp1_b32 s19, 0
	v_cvt_pk_bf16_f32 v162, v32, v33
	v_xor_b32_e32 v32, 0x80000000, v30
	v_xor_b32_e32 v33, 0x80000000, v31
	s_cselect_b32 s19, 0xe000, 0
	v_cvt_pk_bf16_f32 v163, v32, v33
	v_xor_b32_e32 v32, 0x80000000, v24
	v_xor_b32_e32 v33, 0x80000000, v25
	s_add_i32 s19, s19, 0
	v_cvt_pk_bf16_f32 v164, v32, v33
	v_xor_b32_e32 v32, 0x80000000, v26
	v_xor_b32_e32 v33, 0x80000000, v27
	v_and_b32_e32 v43, -16, v40
	v_cvt_pk_bf16_f32 v165, v32, v33
	v_lshlrev_b32_e32 v32, 4, v135
	v_lshl_add_u32 v33, v135, 8, s19
	v_add_u32_e32 v170, 64, v43
	v_add_u32_e32 v172, 0x80, v43
	v_add_u32_e32 v186, 0xc0, v43
	v_xad_u32 v137, v32, v43, v33
	v_xad_u32 v171, v170, v32, v33
	v_xad_u32 v172, v172, v32, v33
	v_xad_u32 v210, v186, v32, v33
	v_lshlrev_b32_e32 v138, 16, v38
	v_and_b32_e32 v139, 0xffff0000, v38
	v_lshlrev_b32_e32 v140, 16, v39
	v_and_b32_e32 v141, 0xffff0000, v39
	v_lshlrev_b32_e32 v42, 3, v40
	ds_read_b128 v[38:41], v137
	ds_read_b128 v[166:169], v171
	ds_read_b128 v[182:185], v172
	ds_read_b128 v[186:189], v210
	ds_read_b128 v[190:193], v137 offset:4096
	ds_read_b128 v[194:197], v171 offset:4096
	ds_read_b128 v[198:201], v172 offset:4096
	ds_read_b128 v[202:205], v210 offset:4096
	v_lshlrev_b32_e32 v142, 16, v34
	v_and_b32_e32 v143, 0xffff0000, v34
	v_lshlrev_b32_e32 v144, 16, v35
	v_and_b32_e32 v145, 0xffff0000, v35
	v_lshlrev_b32_e32 v34, 16, v36
	v_and_b32_e32 v35, 0xffff0000, v36
	v_lshlrev_b32_e32 v36, 16, v37
	v_and_b32_e32 v37, 0xffff0000, v37
	s_waitcnt lgkmcnt(7)
	v_mfma_f32_16x16x32_bf16 v[38:41], v[38:41], v[150:153], v[138:141]
	s_waitcnt lgkmcnt(6)
	v_mfma_f32_16x16x32_bf16 v[38:41], v[166:169], v[154:157], v[38:41]
	s_waitcnt lgkmcnt(5)
	v_mfma_f32_16x16x32_bf16 v[38:41], v[182:185], v[158:161], v[38:41]
	s_waitcnt lgkmcnt(4)
	v_mfma_f32_16x16x32_bf16 v[38:41], v[186:189], v[162:165], v[38:41]
	ds_read_b128 v[138:141], v137 offset:8192
	ds_read_b128 v[166:169], v171 offset:8192
	ds_read_b128 v[182:185], v172 offset:8192
	ds_read_b128 v[186:189], v210 offset:8192
	s_waitcnt lgkmcnt(7)
	v_mfma_f32_16x16x32_bf16 v[142:145], v[190:193], v[150:153], v[142:145]
	s_waitcnt lgkmcnt(6)
	v_mfma_f32_16x16x32_bf16 v[142:145], v[194:197], v[154:157], v[142:145]
	s_waitcnt lgkmcnt(5)
	v_mfma_f32_16x16x32_bf16 v[142:145], v[198:201], v[158:161], v[142:145]
	s_waitcnt lgkmcnt(4)
	v_mfma_f32_16x16x32_bf16 v[142:145], v[202:205], v[162:165], v[142:145]
	ds_read_b128 v[190:193], v137 offset:12288
	ds_read_b128 v[194:197], v171 offset:12288
	ds_read_b128 v[198:201], v172 offset:12288
	ds_read_b128 v[202:205], v210 offset:12288
	s_waitcnt lgkmcnt(7)
	v_mfma_f32_16x16x32_bf16 v[32:35], v[138:141], v[150:153], v[34:37]
	s_waitcnt lgkmcnt(6)
	v_mfma_f32_16x16x32_bf16 v[32:35], v[166:169], v[154:157], v[32:35]
	s_waitcnt lgkmcnt(5)
	v_mfma_f32_16x16x32_bf16 v[32:35], v[182:185], v[158:161], v[32:35]
	s_waitcnt lgkmcnt(4)
	v_mfma_f32_16x16x32_bf16 v[32:35], v[186:189], v[162:165], v[32:35]
	ds_read_b128 v[138:141], v137 offset:16384
	ds_read_b128 v[166:169], v171 offset:16384
	ds_read_b128 v[182:185], v172 offset:16384
	ds_read_b128 v[186:189], v210 offset:16384
	s_waitcnt lgkmcnt(7)
	v_mfma_f32_16x16x32_bf16 v[146:149], v[190:193], v[150:153], v[146:149]
	s_waitcnt lgkmcnt(6)
	v_mfma_f32_16x16x32_bf16 v[146:149], v[194:197], v[154:157], v[146:149]
	s_waitcnt lgkmcnt(5)
	v_mfma_f32_16x16x32_bf16 v[146:149], v[198:201], v[158:161], v[146:149]
	s_waitcnt lgkmcnt(4)
	v_mfma_f32_16x16x32_bf16 v[146:149], v[202:205], v[162:165], v[146:149]
	ds_read_b128 v[190:193], v137 offset:20480
	ds_read_b128 v[194:197], v171 offset:20480
	ds_read_b128 v[198:201], v172 offset:20480
	ds_read_b128 v[202:205], v210 offset:20480
	v_xor_b32_e32 v153, 0x80008000, v153
	v_xor_b32_e32 v152, 0x80008000, v152
	v_xor_b32_e32 v151, 0x80008000, v151
	v_xor_b32_e32 v150, 0x80008000, v150
	v_xor_b32_e32 v157, 0x80008000, v157
	v_xor_b32_e32 v156, 0x80008000, v156
	s_waitcnt lgkmcnt(7)
	v_mfma_f32_16x16x32_bf16 v[138:141], v[138:141], v[150:153], 0
	v_xor_b32_e32 v155, 0x80008000, v155
	v_xor_b32_e32 v154, 0x80008000, v154
	v_xor_b32_e32 v161, 0x80008000, v161
	v_xor_b32_e32 v160, 0x80008000, v160
	s_waitcnt lgkmcnt(6)
	v_mfma_f32_16x16x32_bf16 v[138:141], v[166:169], v[154:157], v[138:141]
	v_xor_b32_e32 v159, 0x80008000, v159
	v_xor_b32_e32 v158, 0x80008000, v158
	v_xor_b32_e32 v165, 0x80008000, v165
	v_xor_b32_e32 v164, 0x80008000, v164
	s_waitcnt lgkmcnt(5)
	v_mfma_f32_16x16x32_bf16 v[138:141], v[182:185], v[158:161], v[138:141]
	v_xor_b32_e32 v163, 0x80008000, v163
	v_xor_b32_e32 v162, 0x80008000, v162
	s_waitcnt lgkmcnt(4)
	s_nop 0
	v_mfma_f32_16x16x32_bf16 v[138:141], v[186:189], v[162:165], v[138:141]
	ds_read_b128 v[166:169], v137 offset:24576
	ds_read_b128 v[182:185], v171 offset:24576
	ds_read_b128 v[186:189], v172 offset:24576
	ds_read_b128 v[206:209], v210 offset:24576
	s_waitcnt lgkmcnt(7)
	v_mfma_f32_16x16x32_bf16 v[190:193], v[190:193], v[150:153], 0
	s_waitcnt lgkmcnt(6)
	v_mfma_f32_16x16x32_bf16 v[190:193], v[194:197], v[154:157], v[190:193]
	s_waitcnt lgkmcnt(5)
	v_mfma_f32_16x16x32_bf16 v[190:193], v[198:201], v[158:161], v[190:193]
	s_waitcnt lgkmcnt(4)
	v_mfma_f32_16x16x32_bf16 v[190:193], v[202:205], v[162:165], v[190:193]
	ds_read_b128 v[194:197], v137 offset:28672
	ds_read_b128 v[198:201], v171 offset:28672
	ds_read_b128 v[202:205], v172 offset:28672
	ds_read_b128 v[210:213], v210 offset:28672
	s_waitcnt lgkmcnt(7)
	v_mfma_f32_16x16x32_bf16 v[166:169], v[166:169], v[150:153], 0
	v_and_b32_e32 v36, 0x70, v42
	v_lshl_add_u32 v37, v135, 7, s19
	v_xad_u32 v137, v36, v43, v37
	s_waitcnt lgkmcnt(6)
	v_mfma_f32_16x16x32_bf16 v[166:169], v[182:185], v[154:157], v[166:169]
	v_xad_u32 v170, v170, v36, v37
	ds_read_b128 v[182:185], v137 offset:49152
	s_waitcnt lgkmcnt(6)
	v_mfma_f32_16x16x32_bf16 v[166:169], v[186:189], v[158:161], v[166:169]
	s_waitcnt lgkmcnt(5)
	v_mfma_f32_16x16x32_bf16 v[166:169], v[206:209], v[162:165], v[166:169]
	ds_read_b128 v[186:189], v170 offset:49152
	ds_read_b128 v[206:209], v137 offset:51200
	ds_read_b128 v[230:233], v170 offset:51200
	s_waitcnt lgkmcnt(7)
	v_mfma_f32_16x16x32_bf16 v[150:153], v[194:197], v[150:153], 0
	s_waitcnt lgkmcnt(6)
	v_mfma_f32_16x16x32_bf16 v[150:153], v[198:201], v[154:157], v[150:153]
	s_waitcnt lgkmcnt(5)
	v_mfma_f32_16x16x32_bf16 v[150:153], v[202:205], v[158:161], v[150:153]
	ds_read_b128 v[154:157], v137 offset:53248
	ds_read_b128 v[158:161], v137 offset:55296
	ds_read_b128 v[194:197], v170 offset:53248
	ds_read_b128 v[198:201], v170 offset:55296
	s_waitcnt lgkmcnt(8)
	v_mfma_f32_16x16x32_bf16 v[150:153], v[210:213], v[162:165], v[150:153]
	v_cvt_pk_bf16_f32 v162, v38, v39
	v_cvt_pk_bf16_f32 v163, v40, v41
	v_cvt_pk_bf16_f32 v164, v142, v143
	v_cvt_pk_bf16_f32 v165, v144, v145
	v_cvt_pk_bf16_f32 v142, v32, v33
	v_cvt_pk_bf16_f32 v143, v34, v35
	s_waitcnt lgkmcnt(7)
	v_mfma_f32_16x16x32_bf16 v[36:39], v[182:185], v[162:165], v[138:141]
	v_cvt_pk_bf16_f32 v144, v146, v147
	v_cvt_pk_bf16_f32 v145, v148, v149
	s_waitcnt lgkmcnt(5)
	v_mfma_f32_16x16x32_bf16 v[32:35], v[206:209], v[162:165], v[190:193]
	v_mfma_f32_16x16x32_bf16 v[138:141], v[186:189], v[142:145], v[36:39]
	ds_read_b128 v[146:149], v137 offset:32768
	ds_read_b128 v[182:185], v137 offset:34816
	ds_read_b128 v[186:189], v170 offset:32768
	ds_read_b128 v[190:193], v170 offset:34816
	s_waitcnt lgkmcnt(8)
	v_mfma_f32_16x16x32_bf16 v[40:43], v[230:233], v[142:145], v[32:35]
	s_waitcnt lgkmcnt(7)
	v_mfma_f32_16x16x32_bf16 v[32:35], v[154:157], v[162:165], v[166:169]
	s_waitcnt lgkmcnt(5)
	v_mfma_f32_16x16x32_bf16 v[36:39], v[194:197], v[142:145], v[32:35]
	v_mfma_f32_16x16x32_bf16 v[32:35], v[158:161], v[162:165], v[150:153]
	s_nop 2
	ds_read_b128 v[150:153], v137 offset:36864
	ds_read_b128 v[154:157], v170 offset:36864
	ds_read_b128 v[158:161], v137 offset:38912
	ds_read_b128 v[166:169], v170 offset:38912
	s_waitcnt lgkmcnt(8)
	v_mfma_f32_16x16x32_bf16 v[32:35], v[198:201], v[142:145], v[32:35]
	v_mul_f32_e64 v2, v124, v2
	v_mul_f32_e64 v3, v124, v3
	v_pk_mul_f32 v[0:1], v[124:125], v[0:1] op_sel_hi:[0,1]
	v_pk_mul_f32 v[6:7], v[124:125], v[6:7] op_sel_hi:[0,1]
	v_pk_mul_f32 v[4:5], v[124:125], v[4:5] op_sel_hi:[0,1]
	s_waitcnt lgkmcnt(7)
	v_mfma_f32_16x16x32_bf16 v[0:3], v[146:149], v[162:165], v[0:3]
	s_waitcnt lgkmcnt(6)
	v_mfma_f32_16x16x32_bf16 v[4:7], v[182:185], v[162:165], v[4:7]
	s_waitcnt lgkmcnt(5)
	v_mfma_f32_16x16x32_bf16 v[0:3], v[186:189], v[142:145], v[0:3]
	s_waitcnt lgkmcnt(4)
	v_mfma_f32_16x16x32_bf16 v[4:7], v[190:193], v[142:145], v[4:7]
	ds_read_b128 v[146:149], v137 offset:40960
	ds_read_b128 v[182:185], v170 offset:40960
	ds_read_b128 v[186:189], v137 offset:43008
	ds_read_b128 v[190:193], v170 offset:43008
	v_pk_mul_f32 v[10:11], v[124:125], v[10:11] op_sel_hi:[0,1]
	v_pk_mul_f32 v[8:9], v[124:125], v[8:9] op_sel_hi:[0,1]
	v_pk_mul_f32 v[14:15], v[124:125], v[14:15] op_sel_hi:[0,1]
	v_pk_mul_f32 v[12:13], v[124:125], v[12:13] op_sel_hi:[0,1]
	s_waitcnt lgkmcnt(7)
	v_mfma_f32_16x16x32_bf16 v[8:11], v[150:153], v[162:165], v[8:11]
	s_waitcnt lgkmcnt(5)
	v_mfma_f32_16x16x32_bf16 v[12:15], v[158:161], v[162:165], v[12:15]
	v_mfma_f32_16x16x32_bf16 v[8:11], v[154:157], v[142:145], v[8:11]
	s_waitcnt lgkmcnt(4)
	v_mfma_f32_16x16x32_bf16 v[12:15], v[166:169], v[142:145], v[12:15]
	ds_read_b128 v[150:153], v137 offset:45056
	ds_read_b128 v[154:157], v170 offset:45056
	ds_read_b128 v[158:161], v137 offset:47104
	ds_read_b128 v[166:169], v170 offset:47104
	v_pk_mul_f32 v[18:19], v[124:125], v[18:19] op_sel_hi:[0,1]
	v_pk_mul_f32 v[16:17], v[124:125], v[16:17] op_sel_hi:[0,1]
	v_pk_mul_f32 v[22:23], v[124:125], v[22:23] op_sel_hi:[0,1]
	v_pk_mul_f32 v[20:21], v[124:125], v[20:21] op_sel_hi:[0,1]
	s_waitcnt lgkmcnt(7)
	v_mfma_f32_16x16x32_bf16 v[16:19], v[146:149], v[162:165], v[16:19]
	s_waitcnt lgkmcnt(5)
	v_mfma_f32_16x16x32_bf16 v[20:23], v[186:189], v[162:165], v[20:23]
	v_mfma_f32_16x16x32_bf16 v[16:19], v[182:185], v[142:145], v[16:19]
	s_waitcnt lgkmcnt(4)
	v_mfma_f32_16x16x32_bf16 v[20:23], v[190:193], v[142:145], v[20:23]
	s_ashr_i32 s19, s18, 31
	s_lshl_b64 s[20:21], s[18:19], 11
	v_pk_mul_f32 v[30:31], v[124:125], v[30:31] op_sel_hi:[0,1]
	v_pk_mul_f32 v[28:29], v[124:125], v[28:29] op_sel_hi:[0,1]
	v_pk_mul_f32 v[26:27], v[124:125], v[26:27] op_sel_hi:[0,1]
	v_pk_mul_f32 v[24:25], v[124:125], v[24:25] op_sel_hi:[0,1]
	s_add_u32 s20, s23, s20
	s_addc_u32 s21, s62, s21
	s_waitcnt lgkmcnt(3)
	v_mfma_f32_16x16x32_bf16 v[28:31], v[150:153], v[162:165], v[28:31]
	s_andn2_b64 vcc, exec, s[12:13]
	s_waitcnt lgkmcnt(1)
	v_mfma_f32_16x16x32_bf16 v[24:27], v[158:161], v[162:165], v[24:27]
	v_mfma_f32_16x16x32_bf16 v[28:31], v[154:157], v[142:145], v[28:31]
	s_waitcnt lgkmcnt(0)
	v_mfma_f32_16x16x32_bf16 v[24:27], v[166:169], v[142:145], v[24:27]
	s_cbranch_vccnz .Lscan_smp
	s_bitcmp1_b32 s64, 0
	s_mov_b32 s65, 0x20010
	s_cselect_b32 s65, 0x1c000, s65
	v_lshlrev_b32_e32 v137, 10, v136
	s_lshl_b32 s66, s28, 1
	v_lshl_add_u32 v137, v135, 1, v137
	v_lshlrev_b32_e32 v124, 5, v136
	v_lshlrev_b32_e32 v171, 11, v136
	v_xor_b32_e32 v124, s66, v124
	v_add3_u32 v137, v137, v124, s65
	v_lshl_add_u32 v171, v135, 4, v171
	v_cvt_pk_bf16_f32 v124, v138, v138
	ds_write_b16 v137, v124
	v_cvt_pk_bf16_f32 v124, v139, v139
	ds_write_b16 v137, v124 offset:256
	v_cvt_pk_bf16_f32 v124, v140, v140
	ds_write_b16 v137, v124 offset:512
	v_cvt_pk_bf16_f32 v124, v141, v141
	ds_write_b16 v137, v124 offset:768
	v_cvt_pk_bf16_f32 v124, v40, v40
	ds_write_b16 v137, v124 offset:4096
	v_cvt_pk_bf16_f32 v124, v41, v41
	ds_write_b16 v137, v124 offset:4352
	v_cvt_pk_bf16_f32 v124, v42, v42
	ds_write_b16 v137, v124 offset:4608
	v_cvt_pk_bf16_f32 v124, v43, v43
	ds_write_b16 v137, v124 offset:4864
	v_cvt_pk_bf16_f32 v124, v36, v36
	ds_write_b16 v137, v124 offset:8192
	v_cvt_pk_bf16_f32 v124, v37, v37
	ds_write_b16 v137, v124 offset:8448
	v_cvt_pk_bf16_f32 v124, v38, v38
	ds_write_b16 v137, v124 offset:8704
	v_cvt_pk_bf16_f32 v124, v39, v39
	ds_write_b16 v137, v124 offset:8960
	v_cvt_pk_bf16_f32 v124, v32, v32
	ds_write_b16 v137, v124 offset:12288
	v_cvt_pk_bf16_f32 v124, v33, v33
	ds_write_b16 v137, v124 offset:12544
	v_cvt_pk_bf16_f32 v124, v34, v34
	ds_write_b16 v137, v124 offset:12800
	v_cvt_pk_bf16_f32 v124, v35, v35
	ds_write_b16 v137, v124 offset:13056
	s_lshl_b32 s66, s28, 1
	s_and_b32 s66, s66, 0x60
	v_lshlrev_b32_e32 v170, 4, v125
	v_xor_b32_e32 v170, s66, v170
	s_lshl_b32 s66, s28, 6
	s_add_i32 s66, s66, s65
	v_add_u32_e32 v170, s66, v170
	s_lshl_b32 s66, s28, 9
	v_add_u32_e32 v171, s66, v171
	s_add_u32 s58, s20, 0x10000
	s_addc_u32 s59, s21, 0
	s_add_i32 s18, s18, 64
	s_waitcnt vmcnt(0) lgkmcnt(0)
	s_barrier
	ds_read_b128 v[146:149], v170
	ds_read_b128 v[150:153], v170 offset:8192
	v_permlane16_swap_b32_e32 v126, v128
	v_permlane16_swap_b32_e32 v127, v129
	v_permlane16_swap_b32_e32 v130, v132
	v_permlane16_swap_b32_e32 v131, v133
	s_nop 1
	v_permlane32_swap_b32_e32 v126, v128
	v_permlane32_swap_b32_e32 v127, v129
	v_permlane32_swap_b32_e32 v130, v132
	v_permlane32_swap_b32_e32 v131, v133
	s_nop 1
	v_mov_b64_e32 v[38:39], v[126:127]
	v_mov_b64_e32 v[34:35], v[128:129]
	v_mov_b64_e32 v[36:37], v[130:131]
	v_mov_b64_e32 v[32:33], v[132:133]
	v_mov_b32_e32 v124, v134
	s_cmp_eq_u32 s22, s64
	s_mov_b32 s19, s64
	s_waitcnt lgkmcnt(1)
	global_store_dwordx4 v171, v[146:149], s[20:21]
	s_waitcnt lgkmcnt(0)
	global_store_dwordx4 v171, v[150:153], s[58:59]
	s_cbranch_scc1 .LBB0_1083
	s_branch .LBB0_1090
